# SwiGLU GEMM epilogue hand-rewritten: packed f32 ops, two row groups interleaved, saddr stores
# speedup vs baseline: 1.0076x; 1.0076x over previous
.LBB0_249:
	s_mov_b32 s40, s15
	s_mov_b32 s0, s35
	s_mov_b32 s1, s14
	v_lshl_add_u32 v211, s34, 1, v251
	ds_read_b64_tr_b16 v[68:69], v211 offset:24576
	ds_read_b64_tr_b16 v[70:71], v211 offset:25088
	v_add_f32_e32 v67, v98, v99
	v_add_f32_e32 v67, v100, v67
	v_add_f32_e32 v67, v101, v67
	v_add_f32_e32 v67, v102, v67
	v_add_f32_e32 v67, v103, v67
	v_cvt_pk_bf16_f32 v158, v98, v99
	v_cvt_pk_bf16_f32 v159, v100, v101
	s_waitcnt lgkmcnt(9)
	v_mfma_f32_32x32x16_bf16 v[130:145], v[206:209], v[174:177], 0
	ds_read_b64_tr_b16 v[72:73], v211 offset:28672
	ds_read_b64_tr_b16 v[74:75], v211 offset:29184
	v_add_f32_e32 v67, v104, v67
	v_add_f32_e32 v67, v105, v67
	v_add_f32_e32 v67, v106, v67
	v_add_f32_e32 v67, v107, v67
	v_cvt_pk_bf16_f32 v160, v102, v103
	v_cvt_pk_bf16_f32 v161, v104, v105
	s_waitcnt lgkmcnt(10)
	v_mfma_f32_32x32x16_bf16 v[114:129], v[198:201], v[174:177], 0
	ds_read_b64_tr_b16 v[76:77], v211 offset:25600
	ds_read_b64_tr_b16 v[78:79], v211 offset:26112
	v_add_f32_e32 v67, v108, v67
	v_add_f32_e32 v67, v109, v67
	v_add_f32_e32 v67, v110, v67
	v_add_f32_e32 v67, v111, v67
	v_cvt_pk_bf16_f32 v154, v106, v107
	v_cvt_pk_bf16_f32 v155, v108, v109
	s_waitcnt lgkmcnt(11)
	v_mfma_f32_32x32x16_bf16 v[130:145], v[202:205], v[170:173], v[130:145]
	ds_read_b64_tr_b16 v[98:99], v211 offset:29696
	ds_read_b64_tr_b16 v[100:101], v211 offset:30208
	v_add_f32_e32 v67, v112, v67
	v_add_f32_e32 v67, v113, v67
	v_add_f32_e32 v67, v82, v67
	v_add_f32_e32 v67, v83, v67
	v_cvt_pk_bf16_f32 v156, v110, v111
	v_cvt_pk_bf16_f32 v157, v112, v113
	s_waitcnt lgkmcnt(12)
	v_mfma_f32_32x32x16_bf16 v[114:129], v[194:197], v[170:173], v[114:129]
	ds_read_b64_tr_b16 v[102:103], v211 offset:26624
	ds_read_b64_tr_b16 v[104:105], v211 offset:27136
	v_add_f32_e32 v67, v84, v67
	v_add_f32_e32 v67, v85, v67
	v_add_f32_e32 v67, v86, v67
	v_add_f32_e32 v67, v87, v67
	v_cvt_pk_bf16_f32 v150, v82, v83
	v_cvt_pk_bf16_f32 v151, v84, v85
	s_waitcnt lgkmcnt(13)
	v_mfma_f32_32x32x16_bf16 v[130:145], v[190:193], v[166:169], v[130:145]
	ds_read_b64_tr_b16 v[106:107], v211 offset:30720
	ds_read_b64_tr_b16 v[108:109], v211 offset:31232
	v_add_f32_e32 v67, v88, v67
	v_add_f32_e32 v67, v89, v67
	v_add_f32_e32 v67, v90, v67
	v_add_f32_e32 v67, v91, v67
	v_cvt_pk_bf16_f32 v152, v86, v87
	v_cvt_pk_bf16_f32 v153, v88, v89
	s_waitcnt lgkmcnt(14)
	v_mfma_f32_32x32x16_bf16 v[114:129], v[186:189], v[166:169], v[114:129]
	ds_read_b64_tr_b16 v[110:111], v211 offset:27648
	ds_read_b64_tr_b16 v[112:113], v211 offset:28160
	v_add_f32_e32 v67, v92, v67
	v_add_f32_e32 v67, v93, v67
	v_add_f32_e32 v67, v94, v67
	v_add_f32_e32 v67, v95, v67
	v_cvt_pk_bf16_f32 v146, v90, v91
	v_cvt_pk_bf16_f32 v147, v92, v93
	s_waitcnt lgkmcnt(14)
	v_mfma_f32_32x32x16_bf16 v[130:145], v[182:185], v[162:165], v[130:145]
	ds_read_b64_tr_b16 v[88:89], v211 offset:31744
	ds_read_b64_tr_b16 v[90:91], v211 offset:32256
	v_add_f32_e32 v67, v96, v67
	v_add_f32_e32 v67, v97, v67
	v_add_f32_e32 v67, 0, v67
	v_cvt_pk_bf16_f32 v148, v94, v95
	v_cvt_pk_bf16_f32 v149, v96, v97
	v_mfma_f32_32x32x16_bf16 v[114:129], v[178:181], v[162:165], v[114:129]
	v_lshl_add_u64 v[190:191], v[226:227], 0, s[2:3]
	s_add_i32 s14, s14, s18
	v_lshl_add_u64 v[80:81], v[190:191], 0, s[70:71]
	s_mov_b32 s15, m0
	s_mov_b32 m0, s14
	s_nop 0
	global_load_lds_dwordx4 v[80:81], off
	s_mov_b32 m0, s15
	v_lshl_add_u64 v[192:193], v[228:229], 0, s[2:3]
	s_lshl_b32 s14, s40, 1
	v_lshl_add_u64 v[80:81], v[192:193], 0, s[58:59]
	s_add_i32 s14, s14, s19
	s_mov_b32 s15, m0
	s_mov_b32 m0, s14
	s_nop 0
	global_load_lds_dwordx4 v[80:81], off
	s_mov_b32 m0, s15
	v_lshl_add_u64 v[194:195], v[230:231], 0, s[2:3]
	v_lshl_add_u64 v[80:81], v[194:195], 0, s[58:59]
	s_addk_i32 s14, 0x2000
	s_mov_b32 s15, m0
	s_mov_b32 m0, s14
	s_nop 0
	global_load_lds_dwordx4 v[80:81], off
	s_mov_b32 m0, s15
	s_waitcnt lgkmcnt(14)
	v_mfma_f32_32x32x16_bf16 v[34:49], v[158:161], v[68:71], v[34:49]
	v_exp_f32_e32 v130, v130
	v_exp_f32_e32 v131, v131
	ds_read_b64_tr_b16 v[92:93], v211 offset:32768
	ds_read_b64_tr_b16 v[94:95], v211 offset:33280
	s_waitcnt lgkmcnt(14)
	v_mfma_f32_32x32x16_bf16 v[50:65], v[158:161], v[72:75], v[50:65]
	v_exp_f32_e32 v132, v132
	v_exp_f32_e32 v133, v133
	ds_read_b64_tr_b16 v[196:197], v211 offset:36864
	ds_read_b64_tr_b16 v[198:199], v211 offset:37376
	v_add_u32_e32 v68, s40, v249
	ds_read_b128 v[84:87], v68
	ds_read_b128 v[80:83], v68 offset:512
	s_waitcnt lgkmcnt(14)
	v_mfma_f32_32x32x16_bf16 v[34:49], v[154:157], v[76:79], v[34:49]
	v_exp_f32_e32 v134, v134
	v_exp_f32_e32 v135, v135
	ds_read_b64_tr_b16 v[200:201], v211 offset:33792
	ds_read_b64_tr_b16 v[202:203], v211 offset:34304
	ds_read_b128 v[186:189], v68 offset:2048
	ds_read_b128 v[182:185], v68 offset:2560
	v_mfma_f32_32x32x16_bf16 v[50:65], v[154:157], v[98:101], v[50:65]
	v_exp_f32_e32 v136, v136
	v_exp_f32_e32 v137, v137
	ds_read_b64_tr_b16 v[96:97], v211 offset:37888
	ds_read_b64_tr_b16 v[98:99], v211 offset:38400
	ds_read_b128 v[178:181], v68 offset:4096
	ds_read_b128 v[76:79], v68 offset:4608
	s_waitcnt lgkmcnt(14)
	v_mfma_f32_32x32x16_bf16 v[34:49], v[150:153], v[102:105], v[34:49]
	v_exp_f32_e32 v138, v138
	v_exp_f32_e32 v139, v139
	ds_read_b64_tr_b16 v[100:101], v211 offset:34816
	ds_read_b64_tr_b16 v[102:103], v211 offset:35328
	ds_read_b128 v[72:75], v68 offset:6144
	ds_read_b128 v[68:71], v68 offset:6656
	v_mfma_f32_32x32x16_bf16 v[50:65], v[150:153], v[106:109], v[50:65]
	v_exp_f32_e32 v140, v140
	v_exp_f32_e32 v141, v141
	ds_read_b64_tr_b16 v[104:105], v211 offset:38912
	ds_read_b64_tr_b16 v[106:107], v211 offset:39424
	v_mfma_f32_32x32x16_bf16 v[34:49], v[146:149], v[110:113], v[34:49]
	v_exp_f32_e32 v142, v142
	v_exp_f32_e32 v143, v143
	ds_read_b64_tr_b16 v[108:109], v211 offset:35840
	ds_read_b64_tr_b16 v[110:111], v211 offset:36352
	v_mfma_f32_32x32x16_bf16 v[50:65], v[146:149], v[88:91], v[50:65]
	v_exp_f32_e32 v144, v144
	v_exp_f32_e32 v145, v145
	ds_read_b64_tr_b16 v[88:89], v211 offset:39936
	ds_read_b64_tr_b16 v[90:91], v211 offset:40448
	s_waitcnt lgkmcnt(14)
	v_mfma_f32_32x32x16_bf16 v[2:17], v[158:161], v[92:95], v[2:17]
	v_exp_f32_e32 v114, v114
	v_exp_f32_e32 v115, v115
	v_mfma_f32_32x32x16_bf16 v[18:33], v[158:161], v[196:199], v[18:33]
	v_exp_f32_e32 v116, v116
	v_exp_f32_e32 v117, v117
	v_mfma_f32_32x32x16_bf16 v[2:17], v[154:157], v[200:203], v[2:17]
	v_exp_f32_e32 v118, v118
	v_exp_f32_e32 v119, v119
	s_waitcnt lgkmcnt(12)
	v_mfma_f32_32x32x16_bf16 v[18:33], v[154:157], v[96:99], v[18:33]
	v_exp_f32_e32 v120, v120
	v_exp_f32_e32 v121, v121
	s_waitcnt lgkmcnt(8)
	v_mfma_f32_32x32x16_bf16 v[2:17], v[150:153], v[100:103], v[2:17]
	v_exp_f32_e32 v122, v122
	v_exp_f32_e32 v123, v123
	s_waitcnt lgkmcnt(4)
	v_mfma_f32_32x32x16_bf16 v[18:33], v[150:153], v[104:107], v[18:33]
	v_exp_f32_e32 v124, v124
	v_exp_f32_e32 v125, v125
	s_waitcnt lgkmcnt(2)
	v_mfma_f32_32x32x16_bf16 v[2:17], v[146:149], v[108:111], v[2:17]
	v_exp_f32_e32 v126, v126
	v_exp_f32_e32 v127, v127
	s_waitcnt lgkmcnt(0)
	v_mfma_f32_32x32x16_bf16 v[18:33], v[146:149], v[88:91], v[18:33]
	v_exp_f32_e32 v128, v128
	v_exp_f32_e32 v129, v129
	s_waitcnt vmcnt(3) lgkmcnt(0)
	s_barrier
	s_add_i32 s14, s40, 0x2000
	s_cmpk_lg_i32 s40, 0x4000
	s_cselect_b32 s14, s14, 0
	v_lshl_add_u32 v211, s1, 1, v251
	ds_read_b64_tr_b16 v[196:197], v211 offset:24576
	ds_read_b64_tr_b16 v[198:199], v211 offset:25088
	v_mfma_f32_32x32x16_bf16 v[98:113], v[84:87], v[174:177], 0
	v_add_f32_e32 v88, v130, v131
	v_add_f32_e32 v88, v132, v88
	v_add_f32_e32 v88, v133, v88
	v_add_f32_e32 v88, v134, v88
	v_add_f32_e32 v88, v135, v88
	v_cvt_pk_bf16_f32 v158, v130, v131
	v_cvt_pk_bf16_f32 v159, v132, v133
	ds_read_b64_tr_b16 v[130:131], v211 offset:28672
	ds_read_b64_tr_b16 v[132:133], v211 offset:29184
	v_add_f32_e32 v84, v136, v88
	v_add_f32_e32 v84, v137, v84
	v_add_f32_e32 v84, v138, v84
	v_add_f32_e32 v146, v139, v84
	v_mfma_f32_32x32x16_bf16 v[82:97], v[80:83], v[174:177], 0
	v_cvt_pk_bf16_f32 v160, v134, v135
	v_cvt_pk_bf16_f32 v161, v136, v137
	ds_read_b64_tr_b16 v[134:135], v211 offset:25600
	ds_read_b64_tr_b16 v[136:137], v211 offset:26112
	v_mfma_f32_32x32x16_bf16 v[98:113], v[186:189], v[170:173], v[98:113]
	v_add_f32_e32 v80, v140, v146
	v_add_f32_e32 v80, v141, v80
	v_add_f32_e32 v80, v142, v80
	v_add_f32_e32 v80, v143, v80
	v_cvt_pk_bf16_f32 v154, v138, v139
	v_cvt_pk_bf16_f32 v155, v140, v141
	ds_read_b64_tr_b16 v[138:139], v211 offset:29696
	ds_read_b64_tr_b16 v[140:141], v211 offset:30208
	v_mfma_f32_32x32x16_bf16 v[82:97], v[182:185], v[170:173], v[82:97]
	v_add_f32_e32 v80, v144, v80
	v_add_f32_e32 v80, v145, v80
	v_add_f32_e32 v80, v114, v80
	v_add_f32_e32 v80, v115, v80
	v_cvt_pk_bf16_f32 v156, v142, v143
	v_cvt_pk_bf16_f32 v157, v144, v145
	ds_read_b64_tr_b16 v[142:143], v211 offset:26624
	ds_read_b64_tr_b16 v[144:145], v211 offset:27136
	v_mfma_f32_32x32x16_bf16 v[98:113], v[178:181], v[166:169], v[98:113]
	v_add_f32_e32 v80, v116, v80
	v_add_f32_e32 v80, v117, v80
	v_add_f32_e32 v80, v118, v80
	v_add_f32_e32 v80, v119, v80
	v_cvt_pk_bf16_f32 v150, v114, v115
	v_cvt_pk_bf16_f32 v151, v116, v117
	ds_read_b64_tr_b16 v[114:115], v211 offset:30720
	ds_read_b64_tr_b16 v[116:117], v211 offset:31232
	v_mfma_f32_32x32x16_bf16 v[82:97], v[76:79], v[166:169], v[82:97]
	v_add_f32_e32 v76, v120, v80
	v_add_f32_e32 v76, v121, v76
	v_add_f32_e32 v76, v122, v76
	v_add_f32_e32 v80, v123, v76
	v_cvt_pk_bf16_f32 v152, v118, v119
	v_cvt_pk_bf16_f32 v153, v120, v121
	ds_read_b64_tr_b16 v[76:77], v211 offset:27648
	ds_read_b64_tr_b16 v[78:79], v211 offset:28160
	v_mfma_f32_32x32x16_bf16 v[98:113], v[72:75], v[162:165], v[98:113]
	v_add_f32_e32 v72, v124, v80
	v_add_f32_e32 v72, v125, v72
	v_add_f32_e32 v72, v126, v72
	v_add_f32_e32 v80, v127, v72
	v_cvt_pk_bf16_f32 v146, v122, v123
	v_cvt_pk_bf16_f32 v147, v124, v125
	ds_read_b64_tr_b16 v[72:73], v211 offset:31744
	ds_read_b64_tr_b16 v[74:75], v211 offset:32256
	v_mfma_f32_32x32x16_bf16 v[82:97], v[68:71], v[162:165], v[82:97]
	v_add_f32_e32 v68, v128, v80
	v_add_f32_e32 v68, v129, v68
	v_add_f32_e32 v80, 0, v68
	v_cvt_pk_bf16_f32 v148, v126, v127
	v_cvt_pk_bf16_f32 v149, v128, v129
	s_add_i32 s1, s40, s18
	v_lshl_add_u64 v[68:69], v[190:191], 0, s[62:63]
	s_mov_b32 s15, m0
	s_mov_b32 m0, s1
	s_nop 0
	global_load_lds_dwordx4 v[68:69], off
	s_mov_b32 m0, s15
	s_lshl_b32 s1, s14, 1
	v_lshl_add_u64 v[68:69], v[192:193], 0, s[60:61]
	s_add_i32 s1, s1, s19
	s_mov_b32 s15, m0
	s_mov_b32 m0, s1
	s_nop 0
	global_load_lds_dwordx4 v[68:69], off
	s_mov_b32 m0, s15
	v_lshl_add_u64 v[68:69], v[194:195], 0, s[60:61]
	s_addk_i32 s1, 0x2000
	s_mov_b32 s15, m0
	s_mov_b32 m0, s1
	s_nop 0
	global_load_lds_dwordx4 v[68:69], off
	s_mov_b32 m0, s15
	s_waitcnt lgkmcnt(14)
	v_mfma_f32_32x32x16_bf16 v[34:49], v[158:161], v[196:199], v[34:49]
	v_exp_f32_e32 v98, v98
	v_exp_f32_e32 v99, v99
	ds_read_b64_tr_b16 v[68:69], v211 offset:32768
	ds_read_b64_tr_b16 v[70:71], v211 offset:33280
	s_waitcnt lgkmcnt(14)
	v_mfma_f32_32x32x16_bf16 v[50:65], v[158:161], v[130:133], v[50:65]
	v_exp_f32_e32 v100, v100
	v_exp_f32_e32 v101, v101
	ds_read_b64_tr_b16 v[118:119], v211 offset:36864
	ds_read_b64_tr_b16 v[120:121], v211 offset:37376
	v_add_u32_e32 v81, s14, v249
	ds_read_b128 v[206:209], v81
	ds_read_b128 v[198:201], v81 offset:512
	s_waitcnt lgkmcnt(14)
	v_mfma_f32_32x32x16_bf16 v[34:49], v[154:157], v[134:137], v[34:49]
	v_exp_f32_e32 v102, v102
	v_exp_f32_e32 v103, v103
	ds_read_b64_tr_b16 v[122:123], v211 offset:33792
	ds_read_b64_tr_b16 v[124:125], v211 offset:34304
	ds_read_b128 v[202:205], v81 offset:2048
	ds_read_b128 v[194:197], v81 offset:2560
	v_mfma_f32_32x32x16_bf16 v[50:65], v[154:157], v[138:141], v[50:65]
	v_exp_f32_e32 v104, v104
	v_exp_f32_e32 v105, v105
	ds_read_b64_tr_b16 v[126:127], v211 offset:37888
	ds_read_b64_tr_b16 v[128:129], v211 offset:38400
	ds_read_b128 v[190:193], v81 offset:4096
	ds_read_b128 v[186:189], v81 offset:4608
	s_waitcnt lgkmcnt(14)
	v_mfma_f32_32x32x16_bf16 v[34:49], v[150:153], v[142:145], v[34:49]
	v_exp_f32_e32 v106, v106
	v_exp_f32_e32 v107, v107
	ds_read_b64_tr_b16 v[130:131], v211 offset:34816
	ds_read_b64_tr_b16 v[132:133], v211 offset:35328
	ds_read_b128 v[182:185], v81 offset:6144
	ds_read_b128 v[178:181], v81 offset:6656
	v_mfma_f32_32x32x16_bf16 v[50:65], v[150:153], v[114:117], v[50:65]
	v_exp_f32_e32 v108, v108
	v_exp_f32_e32 v109, v109
	ds_read_b64_tr_b16 v[114:115], v211 offset:38912
	ds_read_b64_tr_b16 v[116:117], v211 offset:39424
	v_mfma_f32_32x32x16_bf16 v[34:49], v[146:149], v[76:79], v[34:49]
	v_exp_f32_e32 v110, v110
	v_exp_f32_e32 v111, v111
	ds_read_b64_tr_b16 v[76:77], v211 offset:35840
	ds_read_b64_tr_b16 v[78:79], v211 offset:36352
	v_mfma_f32_32x32x16_bf16 v[50:65], v[146:149], v[72:75], v[50:65]
	v_exp_f32_e32 v112, v112
	v_exp_f32_e32 v113, v113
	ds_read_b64_tr_b16 v[72:73], v211 offset:39936
	ds_read_b64_tr_b16 v[74:75], v211 offset:40448
	s_waitcnt lgkmcnt(14)
	v_mfma_f32_32x32x16_bf16 v[2:17], v[158:161], v[68:71], v[2:17]
	v_exp_f32_e32 v82, v82
	v_exp_f32_e32 v83, v83
	v_mfma_f32_32x32x16_bf16 v[18:33], v[158:161], v[118:121], v[18:33]
	v_exp_f32_e32 v84, v84
	v_exp_f32_e32 v85, v85
	v_mfma_f32_32x32x16_bf16 v[2:17], v[154:157], v[122:125], v[2:17]
	v_exp_f32_e32 v86, v86
	v_exp_f32_e32 v87, v87
	s_waitcnt lgkmcnt(12)
	v_mfma_f32_32x32x16_bf16 v[18:33], v[154:157], v[126:129], v[18:33]
	v_exp_f32_e32 v88, v88
	v_exp_f32_e32 v89, v89
	s_waitcnt lgkmcnt(8)
	v_mfma_f32_32x32x16_bf16 v[2:17], v[150:153], v[130:133], v[2:17]
	v_exp_f32_e32 v90, v90
	v_exp_f32_e32 v91, v91
	s_waitcnt lgkmcnt(4)
	v_mfma_f32_32x32x16_bf16 v[18:33], v[150:153], v[114:117], v[18:33]
	v_exp_f32_e32 v92, v92
	v_exp_f32_e32 v93, v93
	s_waitcnt lgkmcnt(2)
	v_mfma_f32_32x32x16_bf16 v[2:17], v[146:149], v[76:79], v[2:17]
	v_exp_f32_e32 v94, v94
	v_exp_f32_e32 v95, v95
	s_waitcnt lgkmcnt(0)
	v_mfma_f32_32x32x16_bf16 v[18:33], v[146:149], v[72:75], v[18:33]
	v_exp_f32_e32 v96, v96
	v_exp_f32_e32 v97, v97
	s_add_i32 s1, s14, 0x2000
	s_cmpk_lg_i32 s14, 0x4000
	s_cselect_b32 s15, s1, 0
	s_add_i32 s35, s35, 2
	s_waitcnt vmcnt(3) lgkmcnt(0)
	s_barrier
	s_add_u32 s2, s2, 0x40000
	v_add_f32_e32 v66, v66, v67
	s_addc_u32 s3, s3, 0
	s_mov_b32 s34, s40
	s_cmp_ge_u32 s35, s29
	v_add_f32_e32 v66, v66, v80
	s_cbranch_scc0 .LBB0_249
	s_add_i32 s50, s0, -5
	s_lshl_b64 s[86:87], s[4:5], 10
	s_add_i32 s0, s50, 1
	s_cmp_lt_u32 s0, s29
	s_cbranch_scc0 .LBB0_254

.LBB0_672:
	v_readlane_b32 s0, v255, 17
	v_lshl_or_b32 v148, s41, 7, v144
	v_readlane_b32 s1, v255, 18
	v_lshl_add_u32 v146, s40, 8, v142
	s_movk_i32 s2, 0x1600
	v_lshlrev_b32_e32 v149, 1, v148
	v_mov_b32_e32 v150, 0xbfb8aa3b
	v_mov_b32_e32 v151, 0xbfb8aa3b
	v_mov_b32_e32 v152, 1.0
	v_mov_b32_e32 v153, 1.0
	v_mad_u32_u24 v140, v146, s2, v149
	v_pk_mul_f32 v[154:155], v[126:127], v[150:151]
	v_pk_mul_f32 v[156:157], v[128:129], v[150:151]
	v_pk_mul_f32 v[158:159], v[118:119], v[150:151]
	v_pk_mul_f32 v[160:161], v[120:121], v[150:151]
	v_pk_mul_f32 v[162:163], v[110:111], v[150:151]
	v_pk_mul_f32 v[164:165], v[112:113], v[150:151]
	v_pk_mul_f32 v[166:167], v[102:103], v[150:151]
	v_pk_mul_f32 v[168:169], v[104:105], v[150:151]
	v_exp_f32_e32 v154, v154
	v_exp_f32_e32 v155, v155
	v_exp_f32_e32 v156, v156
	v_exp_f32_e32 v157, v157
	v_exp_f32_e32 v158, v158
	v_exp_f32_e32 v159, v159
	v_exp_f32_e32 v160, v160
	v_exp_f32_e32 v161, v161
	v_exp_f32_e32 v162, v162
	v_exp_f32_e32 v163, v163
	v_exp_f32_e32 v164, v164
	v_exp_f32_e32 v165, v165
	v_exp_f32_e32 v166, v166
	v_exp_f32_e32 v167, v167
	v_exp_f32_e32 v168, v168
	v_exp_f32_e32 v169, v169
	v_pk_add_f32 v[154:155], v[154:155], v[152:153]
	v_pk_add_f32 v[156:157], v[156:157], v[152:153]
	v_pk_add_f32 v[158:159], v[158:159], v[152:153]
	v_pk_add_f32 v[160:161], v[160:161], v[152:153]
	v_pk_add_f32 v[162:163], v[162:163], v[152:153]
	v_pk_add_f32 v[164:165], v[164:165], v[152:153]
	v_pk_add_f32 v[166:167], v[166:167], v[152:153]
	v_pk_add_f32 v[168:169], v[168:169], v[152:153]
	v_rcp_f32_e32 v154, v154
	v_rcp_f32_e32 v155, v155
	v_rcp_f32_e32 v156, v156
	v_rcp_f32_e32 v157, v157
	v_rcp_f32_e32 v158, v158
	v_rcp_f32_e32 v159, v159
	v_rcp_f32_e32 v160, v160
	v_rcp_f32_e32 v161, v161
	v_rcp_f32_e32 v162, v162
	v_rcp_f32_e32 v163, v163
	v_rcp_f32_e32 v164, v164
	v_rcp_f32_e32 v165, v165
	v_rcp_f32_e32 v166, v166
	v_rcp_f32_e32 v167, v167
	v_rcp_f32_e32 v168, v168
	v_rcp_f32_e32 v169, v169
	v_pk_mul_f32 v[154:155], v[126:127], v[154:155]
	v_pk_mul_f32 v[156:157], v[128:129], v[156:157]
	v_pk_mul_f32 v[158:159], v[118:119], v[158:159]
	v_pk_mul_f32 v[160:161], v[120:121], v[160:161]
	v_pk_mul_f32 v[162:163], v[110:111], v[162:163]
	v_pk_mul_f32 v[164:165], v[112:113], v[164:165]
	v_pk_mul_f32 v[166:167], v[102:103], v[166:167]
	v_pk_mul_f32 v[168:169], v[104:105], v[168:169]
	v_pk_mul_f32 v[154:155], v[154:155], v[122:123]
	v_pk_mul_f32 v[156:157], v[156:157], v[124:125]
	v_pk_mul_f32 v[158:159], v[158:159], v[114:115]
	v_pk_mul_f32 v[160:161], v[160:161], v[116:117]
	v_pk_mul_f32 v[162:163], v[162:163], v[106:107]
	v_pk_mul_f32 v[164:165], v[164:165], v[108:109]
	v_pk_mul_f32 v[166:167], v[166:167], v[98:99]
	v_pk_mul_f32 v[168:169], v[168:169], v[100:101]
	v_cvt_pk_bf16_f32 v154, v154, v155
	v_cvt_pk_bf16_f32 v155, v156, v157
	v_cvt_pk_bf16_f32 v156, v158, v159
	v_cvt_pk_bf16_f32 v157, v160, v161
	v_cvt_pk_bf16_f32 v162, v162, v163
	v_cvt_pk_bf16_f32 v163, v164, v165
	v_cvt_pk_bf16_f32 v164, v166, v167
	v_cvt_pk_bf16_f32 v165, v168, v169
	global_store_dwordx4 v140, v[154:157], s[0:1]
	v_add_u32_e32 v147, 0x16000, v140
	global_store_dwordx4 v147, v[162:165], s[0:1]
	v_pk_mul_f32 v[170:171], v[94:95], v[150:151]
	v_pk_mul_f32 v[172:173], v[96:97], v[150:151]
	v_pk_mul_f32 v[174:175], v[86:87], v[150:151]
	v_pk_mul_f32 v[176:177], v[88:89], v[150:151]
	v_pk_mul_f32 v[178:179], v[78:79], v[150:151]
	v_pk_mul_f32 v[180:181], v[80:81], v[150:151]
	v_pk_mul_f32 v[182:183], v[70:71], v[150:151]
	v_pk_mul_f32 v[184:185], v[72:73], v[150:151]
	v_exp_f32_e32 v170, v170
	v_exp_f32_e32 v171, v171
	v_exp_f32_e32 v172, v172
	v_exp_f32_e32 v173, v173
	v_exp_f32_e32 v174, v174
	v_exp_f32_e32 v175, v175
	v_exp_f32_e32 v176, v176
	v_exp_f32_e32 v177, v177
	v_exp_f32_e32 v178, v178
	v_exp_f32_e32 v179, v179
	v_exp_f32_e32 v180, v180
	v_exp_f32_e32 v181, v181
	v_exp_f32_e32 v182, v182
	v_exp_f32_e32 v183, v183
	v_exp_f32_e32 v184, v184
	v_exp_f32_e32 v185, v185
	v_pk_add_f32 v[170:171], v[170:171], v[152:153]
	v_pk_add_f32 v[172:173], v[172:173], v[152:153]
	v_pk_add_f32 v[174:175], v[174:175], v[152:153]
	v_pk_add_f32 v[176:177], v[176:177], v[152:153]
	v_pk_add_f32 v[178:179], v[178:179], v[152:153]
	v_pk_add_f32 v[180:181], v[180:181], v[152:153]
	v_pk_add_f32 v[182:183], v[182:183], v[152:153]
	v_pk_add_f32 v[184:185], v[184:185], v[152:153]
	v_rcp_f32_e32 v170, v170
	v_rcp_f32_e32 v171, v171
	v_rcp_f32_e32 v172, v172
	v_rcp_f32_e32 v173, v173
	v_rcp_f32_e32 v174, v174
	v_rcp_f32_e32 v175, v175
	v_rcp_f32_e32 v176, v176
	v_rcp_f32_e32 v177, v177
	v_rcp_f32_e32 v178, v178
	v_rcp_f32_e32 v179, v179
	v_rcp_f32_e32 v180, v180
	v_rcp_f32_e32 v181, v181
	v_rcp_f32_e32 v182, v182
	v_rcp_f32_e32 v183, v183
	v_rcp_f32_e32 v184, v184
	v_rcp_f32_e32 v185, v185
	v_pk_mul_f32 v[170:171], v[94:95], v[170:171]
	v_pk_mul_f32 v[172:173], v[96:97], v[172:173]
	v_pk_mul_f32 v[174:175], v[86:87], v[174:175]
	v_pk_mul_f32 v[176:177], v[88:89], v[176:177]
	v_pk_mul_f32 v[178:179], v[78:79], v[178:179]
	v_pk_mul_f32 v[180:181], v[80:81], v[180:181]
	v_pk_mul_f32 v[182:183], v[70:71], v[182:183]
	v_pk_mul_f32 v[184:185], v[72:73], v[184:185]
	v_pk_mul_f32 v[170:171], v[170:171], v[90:91]
	v_pk_mul_f32 v[172:173], v[172:173], v[92:93]
	v_pk_mul_f32 v[174:175], v[174:175], v[82:83]
	v_pk_mul_f32 v[176:177], v[176:177], v[84:85]
	v_pk_mul_f32 v[178:179], v[178:179], v[74:75]
	v_pk_mul_f32 v[180:181], v[180:181], v[76:77]
	v_pk_mul_f32 v[182:183], v[182:183], v[66:67]
	v_pk_mul_f32 v[184:185], v[184:185], v[68:69]
	v_cvt_pk_bf16_f32 v170, v170, v171
	v_cvt_pk_bf16_f32 v171, v172, v173
	v_cvt_pk_bf16_f32 v172, v174, v175
	v_cvt_pk_bf16_f32 v173, v176, v177
	v_cvt_pk_bf16_f32 v178, v178, v179
	v_cvt_pk_bf16_f32 v179, v180, v181
	v_cvt_pk_bf16_f32 v180, v182, v183
	v_cvt_pk_bf16_f32 v181, v184, v185
	v_add_u32_e32 v141, 0x2c000, v140
	global_store_dwordx4 v141, v[170:173], s[0:1]
	v_add_u32_e32 v147, 0x42000, v140
	global_store_dwordx4 v147, v[178:181], s[0:1]
	v_pk_mul_f32 v[186:187], v[62:63], v[150:151]
	v_pk_mul_f32 v[188:189], v[64:65], v[150:151]
	v_pk_mul_f32 v[190:191], v[54:55], v[150:151]
	v_pk_mul_f32 v[192:193], v[56:57], v[150:151]
	v_pk_mul_f32 v[194:195], v[46:47], v[150:151]
	v_pk_mul_f32 v[196:197], v[48:49], v[150:151]
	v_pk_mul_f32 v[198:199], v[38:39], v[150:151]
	v_pk_mul_f32 v[200:201], v[40:41], v[150:151]
	v_exp_f32_e32 v186, v186
	v_exp_f32_e32 v187, v187
	v_exp_f32_e32 v188, v188
	v_exp_f32_e32 v189, v189
	v_exp_f32_e32 v190, v190
	v_exp_f32_e32 v191, v191
	v_exp_f32_e32 v192, v192
	v_exp_f32_e32 v193, v193
	v_exp_f32_e32 v194, v194
	v_exp_f32_e32 v195, v195
	v_exp_f32_e32 v196, v196
	v_exp_f32_e32 v197, v197
	v_exp_f32_e32 v198, v198
	v_exp_f32_e32 v199, v199
	v_exp_f32_e32 v200, v200
	v_exp_f32_e32 v201, v201
	v_pk_add_f32 v[186:187], v[186:187], v[152:153]
	v_pk_add_f32 v[188:189], v[188:189], v[152:153]
	v_pk_add_f32 v[190:191], v[190:191], v[152:153]
	v_pk_add_f32 v[192:193], v[192:193], v[152:153]
	v_pk_add_f32 v[194:195], v[194:195], v[152:153]
	v_pk_add_f32 v[196:197], v[196:197], v[152:153]
	v_pk_add_f32 v[198:199], v[198:199], v[152:153]
	v_pk_add_f32 v[200:201], v[200:201], v[152:153]
	v_rcp_f32_e32 v186, v186
	v_rcp_f32_e32 v187, v187
	v_rcp_f32_e32 v188, v188
	v_rcp_f32_e32 v189, v189
	v_rcp_f32_e32 v190, v190
	v_rcp_f32_e32 v191, v191
	v_rcp_f32_e32 v192, v192
	v_rcp_f32_e32 v193, v193
	v_rcp_f32_e32 v194, v194
	v_rcp_f32_e32 v195, v195
	v_rcp_f32_e32 v196, v196
	v_rcp_f32_e32 v197, v197
	v_rcp_f32_e32 v198, v198
	v_rcp_f32_e32 v199, v199
	v_rcp_f32_e32 v200, v200
	v_rcp_f32_e32 v201, v201
	v_pk_mul_f32 v[186:187], v[62:63], v[186:187]
	v_pk_mul_f32 v[188:189], v[64:65], v[188:189]
	v_pk_mul_f32 v[190:191], v[54:55], v[190:191]
	v_pk_mul_f32 v[192:193], v[56:57], v[192:193]
	v_pk_mul_f32 v[194:195], v[46:47], v[194:195]
	v_pk_mul_f32 v[196:197], v[48:49], v[196:197]
	v_pk_mul_f32 v[198:199], v[38:39], v[198:199]
	v_pk_mul_f32 v[200:201], v[40:41], v[200:201]
	v_pk_mul_f32 v[186:187], v[186:187], v[58:59]
	v_pk_mul_f32 v[188:189], v[188:189], v[60:61]
	v_pk_mul_f32 v[190:191], v[190:191], v[50:51]
	v_pk_mul_f32 v[192:193], v[192:193], v[52:53]
	v_pk_mul_f32 v[194:195], v[194:195], v[42:43]
	v_pk_mul_f32 v[196:197], v[196:197], v[44:45]
	v_pk_mul_f32 v[198:199], v[198:199], v[34:35]
	v_pk_mul_f32 v[200:201], v[200:201], v[36:37]
	v_cvt_pk_bf16_f32 v186, v186, v187
	v_cvt_pk_bf16_f32 v187, v188, v189
	v_cvt_pk_bf16_f32 v188, v190, v191
	v_cvt_pk_bf16_f32 v189, v192, v193
	v_cvt_pk_bf16_f32 v194, v194, v195
	v_cvt_pk_bf16_f32 v195, v196, v197
	v_cvt_pk_bf16_f32 v196, v198, v199
	v_cvt_pk_bf16_f32 v197, v200, v201
	v_add_u32_e32 v141, 0xb0000, v140
	global_store_dwordx4 v141, v[186:189], s[0:1]
	v_add_u32_e32 v147, 0xc6000, v140
	global_store_dwordx4 v147, v[194:197], s[0:1]
	v_pk_mul_f32 v[154:155], v[30:31], v[150:151]
	v_pk_mul_f32 v[156:157], v[32:33], v[150:151]
	v_pk_mul_f32 v[158:159], v[22:23], v[150:151]
	v_pk_mul_f32 v[160:161], v[24:25], v[150:151]
	v_pk_mul_f32 v[162:163], v[14:15], v[150:151]
	v_pk_mul_f32 v[164:165], v[16:17], v[150:151]
	v_pk_mul_f32 v[166:167], v[6:7], v[150:151]
	v_pk_mul_f32 v[168:169], v[8:9], v[150:151]
	v_exp_f32_e32 v154, v154
	v_exp_f32_e32 v155, v155
	v_exp_f32_e32 v156, v156
	v_exp_f32_e32 v157, v157
	v_exp_f32_e32 v158, v158
	v_exp_f32_e32 v159, v159
	v_exp_f32_e32 v160, v160
	v_exp_f32_e32 v161, v161
	v_exp_f32_e32 v162, v162
	v_exp_f32_e32 v163, v163
	v_exp_f32_e32 v164, v164
	v_exp_f32_e32 v165, v165
	v_exp_f32_e32 v166, v166
	v_exp_f32_e32 v167, v167
	v_exp_f32_e32 v168, v168
	v_exp_f32_e32 v169, v169
	v_pk_add_f32 v[154:155], v[154:155], v[152:153]
	v_pk_add_f32 v[156:157], v[156:157], v[152:153]
	v_pk_add_f32 v[158:159], v[158:159], v[152:153]
	v_pk_add_f32 v[160:161], v[160:161], v[152:153]
	v_pk_add_f32 v[162:163], v[162:163], v[152:153]
	v_pk_add_f32 v[164:165], v[164:165], v[152:153]
	v_pk_add_f32 v[166:167], v[166:167], v[152:153]
	v_pk_add_f32 v[168:169], v[168:169], v[152:153]
	v_rcp_f32_e32 v154, v154
	v_rcp_f32_e32 v155, v155
	v_rcp_f32_e32 v156, v156
	v_rcp_f32_e32 v157, v157
	v_rcp_f32_e32 v158, v158
	v_rcp_f32_e32 v159, v159
	v_rcp_f32_e32 v160, v160
	v_rcp_f32_e32 v161, v161
	v_rcp_f32_e32 v162, v162
	v_rcp_f32_e32 v163, v163
	v_rcp_f32_e32 v164, v164
	v_rcp_f32_e32 v165, v165
	v_rcp_f32_e32 v166, v166
	v_rcp_f32_e32 v167, v167
	v_rcp_f32_e32 v168, v168
	v_rcp_f32_e32 v169, v169
	v_pk_mul_f32 v[154:155], v[30:31], v[154:155]
	v_pk_mul_f32 v[156:157], v[32:33], v[156:157]
	v_pk_mul_f32 v[158:159], v[22:23], v[158:159]
	v_pk_mul_f32 v[160:161], v[24:25], v[160:161]
	v_pk_mul_f32 v[162:163], v[14:15], v[162:163]
	v_pk_mul_f32 v[164:165], v[16:17], v[164:165]
	v_pk_mul_f32 v[166:167], v[6:7], v[166:167]
	v_pk_mul_f32 v[168:169], v[8:9], v[168:169]
	v_pk_mul_f32 v[154:155], v[154:155], v[26:27]
	v_pk_mul_f32 v[156:157], v[156:157], v[28:29]
	v_pk_mul_f32 v[158:159], v[158:159], v[18:19]
	v_pk_mul_f32 v[160:161], v[160:161], v[20:21]
	v_pk_mul_f32 v[162:163], v[162:163], v[10:11]
	v_pk_mul_f32 v[164:165], v[164:165], v[12:13]
	v_pk_mul_f32 v[166:167], v[166:167], v[2:3]
	v_pk_mul_f32 v[168:169], v[168:169], v[4:5]
	v_cvt_pk_bf16_f32 v154, v154, v155
	v_cvt_pk_bf16_f32 v155, v156, v157
	v_cvt_pk_bf16_f32 v156, v158, v159
	v_cvt_pk_bf16_f32 v157, v160, v161
	v_cvt_pk_bf16_f32 v162, v162, v163
	v_cvt_pk_bf16_f32 v163, v164, v165
	v_cvt_pk_bf16_f32 v164, v166, v167
	v_cvt_pk_bf16_f32 v165, v168, v169
	v_add_u32_e32 v141, 0xdc000, v140
	global_store_dwordx4 v141, v[154:157], s[0:1]
	v_add_u32_e32 v147, 0xf2000, v140
	global_store_dwordx4 v147, v[162:165], s[0:1]
	s_nop 0
	s_and_b64 vcc, exec, s[4:5]
	s_mov_b64 s[0:1], -1
	s_cbranch_vccnz .LBB0_661
	s_andn2_b64 vcc, exec, s[12:13]
	s_cbranch_vccnz .LBB0_660
	s_barrier
	s_branch .LBB0_660
